# attention window chunks specialised by wave parity: dead score registers skipped (bias, max, exp, pack, 2 PV MFMAs)
# speedup vs baseline: 1.0343x; 1.0037x over previous
.Lwin_even:
	ds_read2_b32 v[82:83], v141 offset0:0 offset1:1
	ds_read2_b32 v[84:85], v141 offset0:2 offset1:3
	ds_read2_b32 v[86:87], v141 offset0:8 offset1:9
	ds_read2_b32 v[88:89], v141 offset0:10 offset1:11
	ds_read2_b32 v[90:91], v141 offset0:16 offset1:17
	ds_read2_b32 v[92:93], v141 offset0:18 offset1:19
	ds_read2_b32 v[94:95], v141 offset0:24 offset1:25
	ds_read2_b32 v[96:97], v141 offset0:26 offset1:27
	ds_read2_b32 v[66:67], v141 offset0:32 offset1:33
	ds_read2_b32 v[68:69], v141 offset0:34 offset1:35
	s_waitcnt lgkmcnt(0)
	v_pk_add_f32 v[82:83], v[50:51], v[82:83]
	v_pk_add_f32 v[84:85], v[52:53], v[84:85]
	v_pk_add_f32 v[86:87], v[54:55], v[86:87]
	v_pk_add_f32 v[88:89], v[56:57], v[88:89]
	v_pk_add_f32 v[90:91], v[58:59], v[90:91]
	v_pk_add_f32 v[92:93], v[60:61], v[92:93]
	v_pk_add_f32 v[94:95], v[62:63], v[94:95]
	v_pk_add_f32 v[96:97], v[64:65], v[96:97]
	v_pk_add_f32 v[66:67], v[34:35], v[66:67]
	v_pk_add_f32 v[68:69], v[36:37], v[68:69]
	v_cndmask_b32_e64 v50, v246, v82, s[4:5]
	v_cndmask_b32_e64 v51, v246, v83, s[8:9]
	v_cndmask_b32_e64 v52, v246, v84, s[12:13]
	v_cndmask_b32_e64 v53, v246, v85, s[16:17]
	v_cndmask_b32_e64 v54, v246, v86, s[20:21]
	v_cndmask_b32_e64 v55, v246, v87, s[24:25]
	v_cndmask_b32_e64 v56, v246, v88, s[28:29]
	v_cndmask_b32_e64 v57, v246, v89, s[34:35]
	v_cndmask_b32_e64 v58, v246, v90, s[38:39]
	v_cndmask_b32_e64 v59, v246, v91, s[42:43]
	v_cndmask_b32_e64 v60, v246, v92, s[46:47]
	v_cndmask_b32_e64 v61, v246, v93, s[50:51]
	v_cndmask_b32_e64 v62, v246, v94, s[54:55]
	v_cndmask_b32_e64 v63, v246, v95, s[58:59]
	v_cndmask_b32_e64 v64, v246, v96, s[62:63]
	v_cndmask_b32_e64 v65, v246, v97, s[66:67]
	v_cndmask_b32_e64 v34, v246, v66, s[6:7]
	v_cndmask_b32_e64 v35, v246, v67, s[10:11]
	v_cndmask_b32_e64 v36, v246, v68, s[14:15]
	v_cndmask_b32_e64 v37, v246, v69, s[18:19]
	s_or_b64 exec, exec, vcc
	v_max3_f32 v66, v50, v51, v52
	v_max3_f32 v67, v53, v54, v55
	v_max3_f32 v68, v56, v57, v58
	v_max3_f32 v69, v59, v60, v61
	v_max3_f32 v66, v66, v62, v63
	v_max3_f32 v67, v67, v64, v65
	v_max3_f32 v68, v68, v34, v35
	v_max3_f32 v69, v69, v36, v37
	v_max3_f32 v66, v66, v67, v68
	v_max_f32_e32 v66, v66, v69
	v_mov_b32_e32 v67, v66
	s_nop 1
	v_permlane32_swap_b32_e32 v66, v67
	v_add_f32_e32 v68, 0x41000000, v190
	v_max_f32_e32 v66, v66, v67
	v_cmp_gt_f32_e32 vcc, v66, v68
	s_cbranch_vccz .Lpv_even
	v_max_f32_e32 v66, v66, v66
	v_max_f32_e32 v67, v190, v190
	v_max_f32_e32 v67, v67, v66
	v_sub_f32_e32 v66, v190, v67
	v_exp_f32_e32 v66, v66
	v_mov_b32_e32 v190, v67
	v_pk_mul_f32 v[16:17], v[16:17], v[66:67] op_sel_hi:[1,0]
	v_pk_mul_f32 v[14:15], v[14:15], v[66:67] op_sel_hi:[1,0]
	v_pk_mul_f32 v[12:13], v[12:13], v[66:67] op_sel_hi:[1,0]
	v_pk_mul_f32 v[10:11], v[10:11], v[66:67] op_sel_hi:[1,0]
	v_pk_mul_f32 v[8:9], v[8:9], v[66:67] op_sel_hi:[1,0]
	v_pk_mul_f32 v[6:7], v[6:7], v[66:67] op_sel_hi:[1,0]
	v_pk_mul_f32 v[4:5], v[4:5], v[66:67] op_sel_hi:[1,0]
	v_pk_mul_f32 v[2:3], v[2:3], v[66:67] op_sel_hi:[1,0]
	v_pk_mul_f32 v[32:33], v[32:33], v[66:67] op_sel_hi:[1,0]
	v_pk_mul_f32 v[30:31], v[30:31], v[66:67] op_sel_hi:[1,0]
	v_pk_mul_f32 v[28:29], v[28:29], v[66:67] op_sel_hi:[1,0]
	v_pk_mul_f32 v[26:27], v[26:27], v[66:67] op_sel_hi:[1,0]
	v_pk_mul_f32 v[24:25], v[24:25], v[66:67] op_sel_hi:[1,0]
	v_pk_mul_f32 v[22:23], v[22:23], v[66:67] op_sel_hi:[1,0]
	v_pk_mul_f32 v[20:21], v[20:21], v[66:67] op_sel_hi:[1,0]
	v_pk_mul_f32 v[18:19], v[18:19], v[66:67] op_sel_hi:[1,0]
	v_mul_f32_e32 v149, v149, v66
.Lpv_even:
	v_pk_add_f32 v[50:51], v[50:51], v[190:191] op_sel_hi:[1,0] neg_lo:[0,1] neg_hi:[0,1]
	v_pk_add_f32 v[52:53], v[52:53], v[190:191] op_sel_hi:[1,0] neg_lo:[0,1] neg_hi:[0,1]
	v_pk_add_f32 v[54:55], v[54:55], v[190:191] op_sel_hi:[1,0] neg_lo:[0,1] neg_hi:[0,1]
	v_pk_add_f32 v[56:57], v[56:57], v[190:191] op_sel_hi:[1,0] neg_lo:[0,1] neg_hi:[0,1]
	v_exp_f32_e32 v50, v50
	v_exp_f32_e32 v51, v51
	v_exp_f32_e32 v52, v52
	v_exp_f32_e32 v53, v53
	v_exp_f32_e32 v54, v54
	v_exp_f32_e32 v55, v55
	v_exp_f32_e32 v56, v56
	v_exp_f32_e32 v57, v57
	v_cvt_pk_bf16_f32 v226, v50, v51
	v_cvt_pk_bf16_f32 v227, v52, v53
	v_cvt_pk_bf16_f32 v228, v54, v55
	v_cvt_pk_bf16_f32 v229, v56, v57
	v_mov_b32_e32 v68, v50
	v_mov_b32_e32 v69, v51
	v_pk_add_f32 v[68:69], v[68:69], v[52:53]
	v_pk_add_f32 v[68:69], v[68:69], v[54:55]
	v_pk_add_f32 v[68:69], v[68:69], v[56:57]
	v_mfma_f32_32x32x16_bf16 v[2:17], v[192:195], v[226:229], v[2:17]
	v_mfma_f32_32x32x16_bf16 v[18:33], v[208:211], v[226:229], v[18:33]
	v_pk_add_f32 v[58:59], v[58:59], v[190:191] op_sel_hi:[1,0] neg_lo:[0,1] neg_hi:[0,1]
	v_pk_add_f32 v[60:61], v[60:61], v[190:191] op_sel_hi:[1,0] neg_lo:[0,1] neg_hi:[0,1]
	v_pk_add_f32 v[62:63], v[62:63], v[190:191] op_sel_hi:[1,0] neg_lo:[0,1] neg_hi:[0,1]
	v_pk_add_f32 v[64:65], v[64:65], v[190:191] op_sel_hi:[1,0] neg_lo:[0,1] neg_hi:[0,1]
	v_exp_f32_e32 v58, v58
	v_exp_f32_e32 v59, v59
	v_exp_f32_e32 v60, v60
	v_exp_f32_e32 v61, v61
	v_exp_f32_e32 v62, v62
	v_exp_f32_e32 v63, v63
	v_exp_f32_e32 v64, v64
	v_exp_f32_e32 v65, v65
	v_cvt_pk_bf16_f32 v230, v58, v59
	v_cvt_pk_bf16_f32 v231, v60, v61
	v_cvt_pk_bf16_f32 v232, v62, v63
	v_cvt_pk_bf16_f32 v233, v64, v65
	v_pk_add_f32 v[68:69], v[68:69], v[58:59]
	v_pk_add_f32 v[68:69], v[68:69], v[60:61]
	v_pk_add_f32 v[68:69], v[68:69], v[62:63]
	v_pk_add_f32 v[68:69], v[68:69], v[64:65]
	v_mfma_f32_32x32x16_bf16 v[2:17], v[196:199], v[230:233], v[2:17]
	v_mfma_f32_32x32x16_bf16 v[18:33], v[214:217], v[230:233], v[18:33]
	v_pk_add_f32 v[34:35], v[34:35], v[190:191] op_sel_hi:[1,0] neg_lo:[0,1] neg_hi:[0,1]
	v_pk_add_f32 v[36:37], v[36:37], v[190:191] op_sel_hi:[1,0] neg_lo:[0,1] neg_hi:[0,1]
	v_exp_f32_e32 v34, v34
	v_exp_f32_e32 v35, v35
	v_exp_f32_e32 v36, v36
	v_exp_f32_e32 v37, v37
	v_cvt_pk_bf16_f32 v234, v34, v35
	v_cvt_pk_bf16_f32 v235, v36, v37
	v_mov_b32_e32 v236, 0
	v_mov_b32_e32 v237, 0
	v_pk_add_f32 v[68:69], v[68:69], v[34:35]
	v_pk_add_f32 v[68:69], v[68:69], v[36:37]
	v_mfma_f32_32x32x16_bf16 v[2:17], v[200:203], v[234:237], v[2:17]
	v_mfma_f32_32x32x16_bf16 v[18:33], v[218:221], v[234:237], v[18:33]
	v_add_f32_e32 v68, v68, v69
	v_add_f32_e32 v149, v149, v68
	s_branch .LBB0_475
.Lwin_odd:
	ds_read2_b32 v[94:95], v141 offset0:24 offset1:25
	ds_read2_b32 v[96:97], v141 offset0:26 offset1:27
	ds_read2_b32 v[66:67], v141 offset0:32 offset1:33
	ds_read2_b32 v[68:69], v141 offset0:34 offset1:35
	ds_read2_b32 v[70:71], v141 offset0:40 offset1:41
	ds_read2_b32 v[72:73], v141 offset0:42 offset1:43
	ds_read2_b32 v[74:75], v141 offset0:48 offset1:49
	ds_read2_b32 v[76:77], v141 offset0:50 offset1:51
	ds_read2_b32 v[78:79], v141 offset0:56 offset1:57
	ds_read2_b32 v[80:81], v141 offset0:58 offset1:59
	s_waitcnt lgkmcnt(0)
	v_pk_add_f32 v[94:95], v[62:63], v[94:95]
	v_pk_add_f32 v[96:97], v[64:65], v[96:97]
	v_pk_add_f32 v[66:67], v[34:35], v[66:67]
	v_pk_add_f32 v[68:69], v[36:37], v[68:69]
	v_pk_add_f32 v[70:71], v[38:39], v[70:71]
	v_pk_add_f32 v[72:73], v[40:41], v[72:73]
	v_pk_add_f32 v[74:75], v[42:43], v[74:75]
	v_pk_add_f32 v[76:77], v[44:45], v[76:77]
	v_pk_add_f32 v[78:79], v[46:47], v[78:79]
	v_pk_add_f32 v[80:81], v[48:49], v[80:81]
	v_cndmask_b32_e64 v62, v246, v94, s[54:55]
	v_cndmask_b32_e64 v63, v246, v95, s[58:59]
	v_cndmask_b32_e64 v64, v246, v96, s[62:63]
	v_cndmask_b32_e64 v65, v246, v97, s[66:67]
	v_cndmask_b32_e64 v34, v246, v66, s[6:7]
	v_cndmask_b32_e64 v35, v246, v67, s[10:11]
	v_cndmask_b32_e64 v36, v246, v68, s[14:15]
	v_cndmask_b32_e64 v37, v246, v69, s[18:19]
	v_cndmask_b32_e64 v38, v246, v70, s[22:23]
	v_cndmask_b32_e64 v39, v246, v71, s[26:27]
	v_cndmask_b32_e64 v40, v246, v72, s[30:31]
	v_cndmask_b32_e64 v41, v246, v73, s[36:37]
	v_cndmask_b32_e64 v42, v246, v74, s[40:41]
	v_cndmask_b32_e64 v43, v246, v75, s[44:45]
	v_cndmask_b32_e64 v44, v246, v76, s[48:49]
	v_cndmask_b32_e64 v45, v246, v77, s[52:53]
	v_cndmask_b32_e64 v46, v246, v78, s[56:57]
	v_cndmask_b32_e64 v47, v246, v79, s[60:61]
	v_cndmask_b32_e64 v48, v246, v80, s[64:65]
	v_cndmask_b32_e64 v49, v246, v81, s[68:69]
	s_or_b64 exec, exec, vcc
	v_max3_f32 v66, v62, v63, v64
	v_max3_f32 v67, v65, v34, v35
	v_max3_f32 v68, v36, v37, v38
	v_max3_f32 v69, v39, v40, v41
	v_max3_f32 v66, v66, v42, v43
	v_max3_f32 v67, v67, v44, v45
	v_max3_f32 v68, v68, v46, v47
	v_max3_f32 v69, v69, v48, v49
	v_max3_f32 v66, v66, v67, v68
	v_max_f32_e32 v66, v66, v69
	v_mov_b32_e32 v67, v66
	s_nop 1
	v_permlane32_swap_b32_e32 v66, v67
	v_add_f32_e32 v68, 0x41000000, v190
	v_max_f32_e32 v66, v66, v67
	v_cmp_gt_f32_e32 vcc, v66, v68
	s_cbranch_vccz .Lpv_odd
	v_max_f32_e32 v66, v66, v66
	v_max_f32_e32 v67, v190, v190
	v_max_f32_e32 v67, v67, v66
	v_sub_f32_e32 v66, v190, v67
	v_exp_f32_e32 v66, v66
	v_mov_b32_e32 v190, v67
	v_pk_mul_f32 v[16:17], v[16:17], v[66:67] op_sel_hi:[1,0]
	v_pk_mul_f32 v[14:15], v[14:15], v[66:67] op_sel_hi:[1,0]
	v_pk_mul_f32 v[12:13], v[12:13], v[66:67] op_sel_hi:[1,0]
	v_pk_mul_f32 v[10:11], v[10:11], v[66:67] op_sel_hi:[1,0]
	v_pk_mul_f32 v[8:9], v[8:9], v[66:67] op_sel_hi:[1,0]
	v_pk_mul_f32 v[6:7], v[6:7], v[66:67] op_sel_hi:[1,0]
	v_pk_mul_f32 v[4:5], v[4:5], v[66:67] op_sel_hi:[1,0]
	v_pk_mul_f32 v[2:3], v[2:3], v[66:67] op_sel_hi:[1,0]
	v_pk_mul_f32 v[32:33], v[32:33], v[66:67] op_sel_hi:[1,0]
	v_pk_mul_f32 v[30:31], v[30:31], v[66:67] op_sel_hi:[1,0]
	v_pk_mul_f32 v[28:29], v[28:29], v[66:67] op_sel_hi:[1,0]
	v_pk_mul_f32 v[26:27], v[26:27], v[66:67] op_sel_hi:[1,0]
	v_pk_mul_f32 v[24:25], v[24:25], v[66:67] op_sel_hi:[1,0]
	v_pk_mul_f32 v[22:23], v[22:23], v[66:67] op_sel_hi:[1,0]
	v_pk_mul_f32 v[20:21], v[20:21], v[66:67] op_sel_hi:[1,0]
	v_pk_mul_f32 v[18:19], v[18:19], v[66:67] op_sel_hi:[1,0]
	v_mul_f32_e32 v149, v149, v66
.Lpv_odd:
	v_pk_add_f32 v[62:63], v[62:63], v[190:191] op_sel_hi:[1,0] neg_lo:[0,1] neg_hi:[0,1]
	v_pk_add_f32 v[64:65], v[64:65], v[190:191] op_sel_hi:[1,0] neg_lo:[0,1] neg_hi:[0,1]
	v_exp_f32_e32 v62, v62
	v_exp_f32_e32 v63, v63
	v_exp_f32_e32 v64, v64
	v_exp_f32_e32 v65, v65
	v_mov_b32_e32 v230, 0
	v_mov_b32_e32 v231, 0
	v_cvt_pk_bf16_f32 v232, v62, v63
	v_cvt_pk_bf16_f32 v233, v64, v65
	v_mov_b32_e32 v68, v62
	v_mov_b32_e32 v69, v63
	v_pk_add_f32 v[68:69], v[68:69], v[64:65]
	v_mfma_f32_32x32x16_bf16 v[2:17], v[196:199], v[230:233], v[2:17]
	v_mfma_f32_32x32x16_bf16 v[18:33], v[214:217], v[230:233], v[18:33]
	v_pk_add_f32 v[34:35], v[34:35], v[190:191] op_sel_hi:[1,0] neg_lo:[0,1] neg_hi:[0,1]
	v_pk_add_f32 v[36:37], v[36:37], v[190:191] op_sel_hi:[1,0] neg_lo:[0,1] neg_hi:[0,1]
	v_pk_add_f32 v[38:39], v[38:39], v[190:191] op_sel_hi:[1,0] neg_lo:[0,1] neg_hi:[0,1]
	v_pk_add_f32 v[40:41], v[40:41], v[190:191] op_sel_hi:[1,0] neg_lo:[0,1] neg_hi:[0,1]
	v_exp_f32_e32 v34, v34
	v_exp_f32_e32 v35, v35
	v_exp_f32_e32 v36, v36
	v_exp_f32_e32 v37, v37
	v_exp_f32_e32 v38, v38
	v_exp_f32_e32 v39, v39
	v_exp_f32_e32 v40, v40
	v_exp_f32_e32 v41, v41
	v_cvt_pk_bf16_f32 v234, v34, v35
	v_cvt_pk_bf16_f32 v235, v36, v37
	v_cvt_pk_bf16_f32 v236, v38, v39
	v_cvt_pk_bf16_f32 v237, v40, v41
	v_pk_add_f32 v[68:69], v[68:69], v[34:35]
	v_pk_add_f32 v[68:69], v[68:69], v[36:37]
	v_pk_add_f32 v[68:69], v[68:69], v[38:39]
	v_pk_add_f32 v[68:69], v[68:69], v[40:41]
	v_mfma_f32_32x32x16_bf16 v[2:17], v[200:203], v[234:237], v[2:17]
	v_mfma_f32_32x32x16_bf16 v[18:33], v[218:221], v[234:237], v[18:33]
	v_pk_add_f32 v[42:43], v[42:43], v[190:191] op_sel_hi:[1,0] neg_lo:[0,1] neg_hi:[0,1]
	v_pk_add_f32 v[44:45], v[44:45], v[190:191] op_sel_hi:[1,0] neg_lo:[0,1] neg_hi:[0,1]
	v_pk_add_f32 v[46:47], v[46:47], v[190:191] op_sel_hi:[1,0] neg_lo:[0,1] neg_hi:[0,1]
	v_pk_add_f32 v[48:49], v[48:49], v[190:191] op_sel_hi:[1,0] neg_lo:[0,1] neg_hi:[0,1]
	v_exp_f32_e32 v42, v42
	v_exp_f32_e32 v43, v43
	v_exp_f32_e32 v44, v44
	v_exp_f32_e32 v45, v45
	v_exp_f32_e32 v46, v46
	v_exp_f32_e32 v47, v47
	v_exp_f32_e32 v48, v48
	v_exp_f32_e32 v49, v49
	v_cvt_pk_bf16_f32 v238, v42, v43
	v_cvt_pk_bf16_f32 v239, v44, v45
	v_cvt_pk_bf16_f32 v240, v46, v47
	v_cvt_pk_bf16_f32 v241, v48, v49
	v_pk_add_f32 v[68:69], v[68:69], v[42:43]
	v_pk_add_f32 v[68:69], v[68:69], v[44:45]
	v_pk_add_f32 v[68:69], v[68:69], v[46:47]
	v_pk_add_f32 v[68:69], v[68:69], v[48:49]
	v_mfma_f32_32x32x16_bf16 v[2:17], v[204:207], v[238:241], v[2:17]
	v_mfma_f32_32x32x16_bf16 v[18:33], v[222:225], v[238:241], v[18:33]
	v_add_f32_e32 v68, v68, v69
	v_add_f32_e32 v149, v149, v68
	s_branch .LBB0_475

.LBB0_478:
	s_or_saveexec_b64 s[72:73], s[72:73]
	v_mov_b64_e32 v[40:41], s[90:91]
	s_xor_b64 exec, exec, s[72:73]
	v_ashrrev_i32_e32 v39, 31, v38
	v_lshlrev_b64 v[34:35], 7, v[38:39]
	v_lshl_add_u64 v[34:35], v[156:157], 0, v[34:35]
	v_ashrrev_i32_e32 v37, 31, v36
	v_mov_b64_e32 v[40:41], v[158:159]
	s_or_b64 exec, exec, s[72:73]
	v_mov_b32_e32 v141, v133
	v_lshlrev_b64 v[36:37], 13, v[36:37]
	v_lshl_add_u64 v[38:39], v[34:35], 0, v[132:133]
	v_mov_b32_e32 v137, v133
	v_lshl_add_u64 v[34:35], v[34:35], 0, v[140:141]
	v_lshl_add_u64 v[36:37], v[40:41], 0, v[36:37]
	v_lshl_add_u64 v[38:39], v[38:39], 0, v[136:137]
	v_lshl_add_u64 v[34:35], v[34:35], 0, v[136:137]
	global_load_dwordx4 v[126:129], v[38:39], off
	global_load_dwordx4 v[122:125], v[34:35], off
	v_lshl_add_u64 v[34:35], v[36:37], 0, v[132:133]
	v_lshl_add_u64 v[34:35], v[34:35], 0, v[136:137]
	v_lshl_add_u64 v[36:37], v[36:37], 0, v[140:141]
	v_lshl_add_u64 v[36:37], v[36:37], 0, v[136:137]
	global_load_dwordx4 v[118:121], v[34:35], off
	global_load_dwordx4 v[114:117], v[36:37], off
	s_cmp_gt_u32 s3, 7
	s_cselect_b64 s[72:73], -1, 0
	s_and_b64 s[94:95], s[0:1], s[72:73]
	v_mov_b32_e32 v66, 0
	s_mov_b64 vcc, -1
	s_and_saveexec_b64 s[76:77], s[94:95]
	v_add_u32_e32 v34, s3, v189
	v_cmp_ge_i32_e32 vcc, v34, v182
	v_cmp_lt_i32_e64 s[72:73], v34, v186
	s_and_b64 s[72:73], vcc, s[72:73]
	s_orn2_b64 vcc, s[72:73], exec
	v_mov_b32_e32 v66, v188
	s_or_b64 exec, exec, s[76:77]
	s_and_saveexec_b64 s[72:73], vcc
	s_cbranch_execz .LBB0_475
	s_bitcmp1_b32 s3, 0
	s_cselect_b32 s3, 0x4800, 0
	v_add_u32_e32 v137, s3, v173
	ds_read_b128 v[192:195], v137
	ds_read_b128 v[208:211], v137 offset:4608
	ds_read_b128 v[196:199], v137 offset:32
	ds_read_b128 v[214:217], v137 offset:4640
	ds_read_b128 v[200:203], v137 offset:64
	ds_read_b128 v[218:221], v137 offset:4672
	ds_read_b128 v[204:207], v137 offset:96
	ds_read_b128 v[222:225], v137 offset:4704
	s_waitcnt lgkmcnt(6)
	v_mfma_f32_32x32x16_bf16 v[50:65], v[192:195], v[98:101], 0
	v_mfma_f32_32x32x16_bf16 v[34:49], v[208:211], v[98:101], 0
	s_waitcnt lgkmcnt(4)
	v_mfma_f32_32x32x16_bf16 v[50:65], v[196:199], v[102:105], v[50:65]
	v_mfma_f32_32x32x16_bf16 v[34:49], v[214:217], v[102:105], v[34:49]
	s_waitcnt lgkmcnt(2)
	v_mfma_f32_32x32x16_bf16 v[50:65], v[200:203], v[106:109], v[50:65]
	v_mfma_f32_32x32x16_bf16 v[34:49], v[218:221], v[106:109], v[34:49]
	s_waitcnt lgkmcnt(0)
	v_mfma_f32_32x32x16_bf16 v[50:65], v[204:207], v[110:113], v[50:65]
	v_mfma_f32_32x32x16_bf16 v[34:49], v[222:225], v[110:113], v[34:49]
	ds_read_b128 v[192:195], v137 offset:9216
	ds_read_b128 v[208:211], v137 offset:13824
	ds_read_b128 v[196:199], v137 offset:9248
	ds_read_b128 v[214:217], v137 offset:13856
	ds_read_b128 v[200:203], v137 offset:9280
	ds_read_b128 v[218:221], v137 offset:13888
	ds_read_b128 v[204:207], v137 offset:9312
	ds_read_b128 v[222:225], v137 offset:13920
	s_and_saveexec_b64 vcc, s[94:95]
	s_cbranch_execz .LBB0_549
	v_lshl_add_u32 v141, v66, 2, v187
	v_add_u32_e32 v141, 0x903c, v141
	v_mov_b32_e32 v246, 0xff800000
	v_readfirstlane_b32 s98, v212
	s_nop 0
	s_bitcmp1_b32 s98, 6
	s_cbranch_scc1 .Lwin_odd
	s_branch .Lwin_even
